# attention tile loop: near-tile block out of line, dead pads and zero adds removed, K-load guard re-compared
# speedup vs baseline: 1.0172x; 1.0113x over previous
.LBB0_168:
	s_lshl_b32 s101, s33, 14
	v_add_u32_e32 v82, s101, v239
	v_add_u32_e32 v102, s101, v240
	ds_read_b128 v[98:101], v82
	ds_read_b128 v[114:117], v82 offset:8192
	ds_read_b128 v[118:121], v102
	s_barrier
	s_cmp_lt_u32 s22, s19
	s_cbranch_scc0 .Lhd_u1e

.LBB0_185:
	s_lshl_b32 s22, s33, 14
	ds_read_b128 v[126:129], v249 offset:49152
	s_waitcnt lgkmcnt(1)
	v_mfma_f32_32x32x16_bf16 v[82:97], v[98:101], v[146:149], v[66:81]
	ds_read_b128 v[122:125], v102 offset:8192
	v_mfma_f32_32x32x16_bf16 v[98:113], v[114:117], v[146:149], v[66:81]
	v_add_u32_e32 v139, s22, v241
	ds_read_b128 v[114:117], v139
	v_mfma_f32_32x32x16_bf16 v[82:97], v[118:121], v[150:153], v[82:97]
	ds_read_b128 v[118:121], v139 offset:8192
	s_waitcnt lgkmcnt(0)
	v_mfma_f32_32x32x16_bf16 v[98:113], v[122:125], v[150:153], v[98:113]
	v_add_u32_e32 v139, s22, v243
	ds_read_b128 v[122:125], v139
	v_mfma_f32_32x32x16_bf16 v[82:97], v[114:117], v[154:157], v[82:97]
	ds_read_b128 v[114:117], v139 offset:8192
	v_mfma_f32_32x32x16_bf16 v[98:113], v[118:121], v[154:157], v[98:113]
	s_waitcnt lgkmcnt(0)
	v_mfma_f32_32x32x16_bf16 v[82:97], v[122:125], v[158:161], v[82:97]
	v_mfma_f32_32x32x16_bf16 v[98:113], v[114:117], v[158:161], v[98:113]
	s_nop 0
	ds_read_b128 v[122:125], v249 offset:53248
	ds_read_b128 v[118:121], v249 offset:57344
	ds_read_b128 v[114:117], v249 offset:61440
	s_add_i32 s22, s21, 64
	s_cmp_le_u32 s22, s20
	s_cbranch_scc0 .Lnear_u1e
.LBB0_188:
	s_waitcnt lgkmcnt(3)
	v_mfma_f32_32x32x16_bf16 v[34:49], v[126:129], v[162:165], v[34:49]
	ds_read_b128 v[126:129], v212 offset:49152
	s_nop 0
	v_exp_f32_e32 v130, v82
	v_exp_f32_e32 v131, v83
	v_add_f32_e32 v132, v1, v130
	v_add_f32_e32 v133, v1, v131
	v_cvt_pk_bf16_f32 v166, v130, v131
	s_waitcnt lgkmcnt(3)
	v_mfma_f32_32x32x16_bf16 v[50:65], v[122:125], v[162:165], v[50:65]
	ds_read_b128 v[122:125], v212 offset:53248
	v_exp_f32_e32 v134, v84
	v_exp_f32_e32 v135, v85
	s_add_i32 s22, s23, 2
	v_add_f32_e32 v130, v132, v134
	v_add_f32_e32 v131, v133, v135
	v_cvt_pk_bf16_f32 v167, v134, v135
	s_cmp_ge_u32 s22, s17
	s_cbranch_scc1 .LBB0_190
	s_lshl_b32 s40, s48, 14
	s_add_i32 m0, s11, s40
	s_add_u32 s100, s8, s80
	s_addc_u32 s101, s9, s81
	global_load_lds_dwordx4 v214, s[100:101]
.LBB0_190:
	s_waitcnt lgkmcnt(3)
	v_mfma_f32_32x32x16_bf16 v[18:33], v[118:121], v[162:165], v[18:33]
	ds_read_b128 v[118:121], v212 offset:57344
	v_exp_f32_e32 v132, v86
	v_exp_f32_e32 v133, v87
	v_add_f32_e32 v130, v130, v132
	v_add_f32_e32 v131, v131, v133
	v_cvt_pk_bf16_f32 v168, v132, v133
	s_waitcnt lgkmcnt(3)
	v_mfma_f32_32x32x16_bf16 v[2:17], v[114:117], v[162:165], v[2:17]
	ds_read_b128 v[114:117], v212 offset:61440
	v_exp_f32_e32 v132, v88
	v_exp_f32_e32 v133, v89
	v_add_f32_e32 v134, v130, v132
	v_add_f32_e32 v131, v131, v133
	v_cvt_pk_bf16_f32 v169, v132, v133
	s_waitcnt lgkmcnt(3)
	v_mfma_f32_32x32x16_bf16 v[34:49], v[126:129], v[170:173], v[34:49]
	v_add_u32_e32 v130, s54, v246
	ds_read_b128 v[126:129], v130 offset:49152
	v_exp_f32_e32 v132, v90
	v_exp_f32_e32 v133, v91
	v_add_f32_e32 v134, v134, v132
	v_add_f32_e32 v135, v131, v133
	v_cvt_pk_bf16_f32 v174, v132, v133
	s_waitcnt lgkmcnt(3)
	v_mfma_f32_32x32x16_bf16 v[50:65], v[122:125], v[170:173], v[50:65]
	ds_read_b128 v[122:125], v130 offset:53248
	v_exp_f32_e32 v133, v92
	v_exp_f32_e32 v136, v93
	v_add_f32_e32 v131, v134, v133
	v_add_f32_e32 v132, v135, v136
	s_cmp_ge_u32 s22, s17
	v_cvt_pk_bf16_f32 v175, v133, v136
	s_cbranch_scc1 .LBB0_192
	s_lshl_b32 s26, s48, 14
	s_add_i32 s26, s11, s26
	s_add_i32 m0, s26, 0x2000
	s_add_u32 s100, s8, s62
	s_addc_u32 s101, s9, s63
	global_load_lds_dwordx4 v214, s[100:101]

.LBB0_208:
	s_add_i32 s26, s33, 1
	s_cmp_lg_u32 s33, 2
	s_cselect_b32 s33, s26, 0
	s_add_i32 s26, s48, 1
	s_cmp_lg_u32 s48, 2
	s_cselect_b32 s48, s26, 0
	s_add_i32 s26, s49, 1
	s_cmp_lg_u32 s49, 2
	s_cselect_b32 s49, s26, 0
	s_add_i32 s26, s31, 1
	s_lshl_b32 s101, s33, 14
	v_add_u32_e32 v82, s101, v239
	v_add_u32_e32 v102, s101, v240
	ds_read_b128 v[98:101], v82
	ds_read_b128 v[114:117], v82 offset:8192
	ds_read_b128 v[118:121], v102
	s_barrier
	s_cmp_lg_u32 s31, 2
	s_cselect_b32 s31, s26, 0
	s_cmp_lt_u32 s23, s19
	s_cbranch_scc0 .Lhd_u1o

.LBB0_225:
	s_lshl_b32 s26, s33, 14
	ds_read_b128 v[126:129], v249 offset:49152
	s_waitcnt lgkmcnt(1)
	v_mfma_f32_32x32x16_bf16 v[82:97], v[98:101], v[146:149], v[66:81]
	ds_read_b128 v[122:125], v102 offset:8192
	v_mfma_f32_32x32x16_bf16 v[98:113], v[114:117], v[146:149], v[66:81]
	v_add_u32_e32 v139, s26, v241
	ds_read_b128 v[114:117], v139
	v_mfma_f32_32x32x16_bf16 v[82:97], v[118:121], v[150:153], v[82:97]
	ds_read_b128 v[118:121], v139 offset:8192
	s_waitcnt lgkmcnt(0)
	v_mfma_f32_32x32x16_bf16 v[98:113], v[122:125], v[150:153], v[98:113]
	v_add_u32_e32 v139, s26, v243
	ds_read_b128 v[122:125], v139
	v_mfma_f32_32x32x16_bf16 v[82:97], v[114:117], v[154:157], v[82:97]
	ds_read_b128 v[114:117], v139 offset:8192
	v_mfma_f32_32x32x16_bf16 v[98:113], v[118:121], v[154:157], v[98:113]
	s_waitcnt lgkmcnt(0)
	v_mfma_f32_32x32x16_bf16 v[82:97], v[122:125], v[158:161], v[82:97]
	v_mfma_f32_32x32x16_bf16 v[98:113], v[114:117], v[158:161], v[98:113]
	s_nop 0
	ds_read_b128 v[122:125], v249 offset:53248
	ds_read_b128 v[118:121], v249 offset:57344
	ds_read_b128 v[114:117], v249 offset:61440
	s_add_i32 s26, s21, 0x80
	s_cmp_le_u32 s26, s20
	s_cbranch_scc0 .Lnear_u1o

.Lnear_u1e:
	v_add_u32_e32 v130, s21, v248
	v_add_u32_e32 v130, 0x11f, v130
	v_and_b32_e32 v130, 0x3ffffffc, v130
	v_lshl_add_u32 v166, v130, 2, v0
	ds_read_b128 v[130:133], v166
	ds_read_b128 v[134:137], v166 offset:16
	ds_read_b128 v[138:141], v166 offset:64
	ds_read_b128 v[142:145], v166 offset:80
	s_waitcnt lgkmcnt(0)
	v_pk_add_f32 v[84:85], v[84:85], v[132:133]
	v_pk_add_f32 v[86:87], v[86:87], v[134:135]
	v_pk_add_f32 v[90:91], v[90:91], v[138:139]
	v_pk_add_f32 v[94:95], v[94:95], v[142:143]
	v_pk_add_f32 v[96:97], v[96:97], v[144:145]
	v_pk_add_f32 v[92:93], v[92:93], v[140:141]
	v_pk_add_f32 v[88:89], v[88:89], v[136:137]
	v_pk_add_f32 v[82:83], v[82:83], v[130:131]
	ds_read_b128 v[130:133], v166 offset:128
	ds_read_b128 v[134:137], v166 offset:144
	ds_read_b128 v[138:141], v166 offset:192
	ds_read_b128 v[142:145], v166 offset:208
	s_waitcnt lgkmcnt(0)
	v_pk_add_f32 v[100:101], v[100:101], v[132:133]
	v_pk_add_f32 v[102:103], v[102:103], v[134:135]
	v_pk_add_f32 v[106:107], v[106:107], v[138:139]
	v_pk_add_f32 v[110:111], v[110:111], v[142:143]
	v_pk_add_f32 v[112:113], v[112:113], v[144:145]
	v_pk_add_f32 v[108:109], v[108:109], v[140:141]
	v_pk_add_f32 v[104:105], v[104:105], v[136:137]
	v_pk_add_f32 v[98:99], v[98:99], v[130:131]
	s_branch .LBB0_188
.Lnear_u1o:
	v_add_u32_e32 v130, s21, v248
	v_add_u32_e32 v130, 0x15f, v130
	v_and_b32_e32 v130, 0x3ffffffc, v130
	v_lshl_add_u32 v162, v130, 2, v0
	ds_read_b128 v[130:133], v162
	ds_read_b128 v[134:137], v162 offset:16
	ds_read_b128 v[138:141], v162 offset:64
	ds_read_b128 v[142:145], v162 offset:80
	s_waitcnt lgkmcnt(0)
	v_pk_add_f32 v[84:85], v[84:85], v[132:133]
	v_pk_add_f32 v[86:87], v[86:87], v[134:135]
	v_pk_add_f32 v[90:91], v[90:91], v[138:139]
	v_pk_add_f32 v[94:95], v[94:95], v[142:143]
	v_pk_add_f32 v[96:97], v[96:97], v[144:145]
	v_pk_add_f32 v[92:93], v[92:93], v[140:141]
	v_pk_add_f32 v[88:89], v[88:89], v[136:137]
	v_pk_add_f32 v[82:83], v[82:83], v[130:131]
	ds_read_b128 v[130:133], v162 offset:128
	ds_read_b128 v[134:137], v162 offset:144
	ds_read_b128 v[138:141], v162 offset:192
	ds_read_b128 v[142:145], v162 offset:208
	s_waitcnt lgkmcnt(0)
	v_pk_add_f32 v[100:101], v[100:101], v[132:133]
	v_pk_add_f32 v[102:103], v[102:103], v[134:135]
	v_pk_add_f32 v[106:107], v[106:107], v[138:139]
	v_pk_add_f32 v[110:111], v[110:111], v[142:143]
	v_pk_add_f32 v[112:113], v[112:113], v[144:145]
	v_pk_add_f32 v[108:109], v[108:109], v[140:141]
	v_pk_add_f32 v[104:105], v[104:105], v[136:137]
	v_pk_add_f32 v[98:99], v[98:99], v[130:131]
	s_branch .LBB0_228

.LBB0_271:
	s_lshl_b32 s101, s31, 14
	v_add_u32_e32 v82, s101, v239
	v_add_u32_e32 v102, s101, v240
	ds_read_b128 v[98:101], v82
	ds_read_b128 v[114:117], v82 offset:8192
	ds_read_b128 v[118:121], v102
	s_barrier
	s_cmp_lt_u32 s21, s19
	s_cbranch_scc0 .Lhd_u2e

.LBB0_288:
	s_lshl_b32 s21, s31, 14
	ds_read_b128 v[126:129], v212 offset:49152
	s_waitcnt lgkmcnt(1)
	v_mfma_f32_32x32x16_bf16 v[82:97], v[98:101], v[146:149], v[66:81]
	ds_read_b128 v[122:125], v102 offset:8192
	v_mfma_f32_32x32x16_bf16 v[98:113], v[114:117], v[146:149], v[66:81]
	v_add_u32_e32 v139, s21, v241
	ds_read_b128 v[114:117], v139
	v_mfma_f32_32x32x16_bf16 v[82:97], v[118:121], v[150:153], v[82:97]
	ds_read_b128 v[118:121], v139 offset:8192
	s_waitcnt lgkmcnt(0)
	v_mfma_f32_32x32x16_bf16 v[98:113], v[122:125], v[150:153], v[98:113]
	v_add_u32_e32 v139, s21, v242
	ds_read_b128 v[122:125], v139
	v_mfma_f32_32x32x16_bf16 v[82:97], v[114:117], v[154:157], v[82:97]
	ds_read_b128 v[114:117], v139 offset:8192
	v_mfma_f32_32x32x16_bf16 v[98:113], v[118:121], v[154:157], v[98:113]
	s_waitcnt lgkmcnt(0)
	v_mfma_f32_32x32x16_bf16 v[82:97], v[122:125], v[158:161], v[82:97]
	v_mfma_f32_32x32x16_bf16 v[98:113], v[114:117], v[158:161], v[98:113]
	s_nop 0
	ds_read_b128 v[122:125], v212 offset:53248
	ds_read_b128 v[118:121], v212 offset:57344
	ds_read_b128 v[114:117], v212 offset:61440
	s_cmp_le_u32 s20, s16
	s_cbranch_scc0 .Lnear_u2e
.LBB0_291:
	s_waitcnt lgkmcnt(3)
	v_mfma_f32_32x32x16_bf16 v[50:65], v[126:129], v[162:165], v[50:65]
	ds_read_b128 v[126:129], v0 offset:49152
	s_nop 1
	v_exp_f32_e32 v130, v82
	v_exp_f32_e32 v131, v83
	v_add_f32_e32 v132, v1, v130
	v_add_f32_e32 v133, v1, v131
	v_cvt_pk_bf16_f32 v166, v130, v131
	s_waitcnt lgkmcnt(3)
	v_mfma_f32_32x32x16_bf16 v[34:49], v[122:125], v[162:165], v[34:49]
	ds_read_b128 v[122:125], v0 offset:53248
	v_exp_f32_e32 v134, v84
	v_exp_f32_e32 v135, v85
	s_add_i32 s21, s22, 2
	v_add_f32_e32 v130, v132, v134
	v_add_f32_e32 v131, v133, v135
	v_cvt_pk_bf16_f32 v167, v134, v135
	s_cmp_ge_u32 s21, s18
	s_cbranch_scc1 .LBB0_293
	s_lshl_b32 s37, s28, 14
	s_add_i32 m0, s10, s37
	s_add_u32 s100, s8, s80
	s_addc_u32 s101, s9, s81
	global_load_lds_dwordx4 v214, s[100:101]
.LBB0_293:
	s_waitcnt lgkmcnt(3)
	v_mfma_f32_32x32x16_bf16 v[18:33], v[118:121], v[162:165], v[18:33]
	ds_read_b128 v[118:121], v0 offset:57344
	v_exp_f32_e32 v132, v86
	v_exp_f32_e32 v133, v87
	v_add_f32_e32 v130, v130, v132
	v_add_f32_e32 v131, v131, v133
	v_cvt_pk_bf16_f32 v168, v132, v133
	s_waitcnt lgkmcnt(3)
	v_mfma_f32_32x32x16_bf16 v[2:17], v[114:117], v[162:165], v[2:17]
	ds_read_b128 v[114:117], v0 offset:61440
	v_exp_f32_e32 v0, v88
	v_exp_f32_e32 v132, v89
	v_add_f32_e32 v130, v130, v0
	v_add_f32_e32 v131, v131, v132
	v_cvt_pk_bf16_f32 v169, v0, v132
	s_waitcnt lgkmcnt(3)
	v_mfma_f32_32x32x16_bf16 v[50:65], v[126:129], v[170:173], v[50:65]
	v_add_u32_e32 v0, s36, v247
	ds_read_b128 v[126:129], v0 offset:49152
	v_exp_f32_e32 v132, v90
	v_exp_f32_e32 v133, v91
	v_add_f32_e32 v130, v130, v132
	v_add_f32_e32 v131, v131, v133
	v_cvt_pk_bf16_f32 v174, v132, v133
	s_waitcnt lgkmcnt(3)
	v_mfma_f32_32x32x16_bf16 v[34:49], v[122:125], v[170:173], v[34:49]
	ds_read_b128 v[122:125], v0 offset:53248
	v_exp_f32_e32 v132, v92
	v_exp_f32_e32 v133, v93
	v_add_f32_e32 v130, v130, v132
	v_add_f32_e32 v131, v131, v133
	s_cmp_ge_u32 s21, s18
	v_cvt_pk_bf16_f32 v175, v132, v133
	s_cbranch_scc1 .LBB0_295
	s_lshl_b32 s26, s28, 14
	s_add_i32 s26, s10, s26
	s_add_i32 m0, s26, 0x2000
	s_add_u32 s100, s8, s62
	s_addc_u32 s101, s9, s63
	global_load_lds_dwordx4 v214, s[100:101]

.LBB0_311:
	s_add_i32 s26, s31, 1
	s_cmp_lg_u32 s31, 2
	s_cselect_b32 s31, s26, 0
	s_add_i32 s26, s28, 1
	s_cmp_lg_u32 s28, 2
	s_cselect_b32 s28, s26, 0
	s_add_i32 s26, s33, 1
	s_cmp_lg_u32 s33, 2
	s_cselect_b32 s33, s26, 0
	s_add_i32 s26, s23, 1
	s_lshl_b32 s101, s31, 14
	v_add_u32_e32 v82, s101, v239
	v_add_u32_e32 v102, s101, v240
	ds_read_b128 v[98:101], v82
	ds_read_b128 v[114:117], v82 offset:8192
	ds_read_b128 v[118:121], v102
	s_barrier
	s_cmp_lg_u32 s23, 2
	s_cselect_b32 s23, s26, 0
	s_cmp_lt_u32 s22, s19
	s_cbranch_scc0 .Lhd_u2o

.LBB0_328:
	s_lshl_b32 s26, s31, 14
	ds_read_b128 v[126:129], v212 offset:49152
	s_waitcnt lgkmcnt(1)
	v_mfma_f32_32x32x16_bf16 v[82:97], v[98:101], v[146:149], v[66:81]
	ds_read_b128 v[122:125], v102 offset:8192
	v_mfma_f32_32x32x16_bf16 v[98:113], v[114:117], v[146:149], v[66:81]
	v_add_u32_e32 v139, s26, v241
	ds_read_b128 v[114:117], v139
	v_mfma_f32_32x32x16_bf16 v[82:97], v[118:121], v[150:153], v[82:97]
	ds_read_b128 v[118:121], v139 offset:8192
	s_waitcnt lgkmcnt(0)
	v_mfma_f32_32x32x16_bf16 v[98:113], v[122:125], v[150:153], v[98:113]
	v_add_u32_e32 v139, s26, v242
	ds_read_b128 v[122:125], v139
	v_mfma_f32_32x32x16_bf16 v[82:97], v[114:117], v[154:157], v[82:97]
	ds_read_b128 v[114:117], v139 offset:8192
	v_mfma_f32_32x32x16_bf16 v[98:113], v[118:121], v[154:157], v[98:113]
	s_waitcnt lgkmcnt(0)
	v_mfma_f32_32x32x16_bf16 v[82:97], v[122:125], v[158:161], v[82:97]
	v_mfma_f32_32x32x16_bf16 v[98:113], v[114:117], v[158:161], v[98:113]
	s_nop 0
	ds_read_b128 v[122:125], v212 offset:53248
	ds_read_b128 v[118:121], v212 offset:57344
	ds_read_b128 v[114:117], v212 offset:61440
	s_add_i32 s26, s20, 64
	s_cmp_le_u32 s26, s16
	s_cbranch_scc0 .Lnear_u2o

.Lnear_u2e:
	v_add3_u32 v130, v249, s20, 47
	v_and_b32_e32 v130, 0x3ffffffc, v130
	v_lshl_add_u32 v166, v130, 2, v244
	ds_read_b128 v[130:133], v166
	ds_read_b128 v[134:137], v166 offset:16
	ds_read_b128 v[138:141], v166 offset:64
	ds_read_b128 v[142:145], v166 offset:80
	s_waitcnt lgkmcnt(0)
	v_pk_add_f32 v[84:85], v[84:85], v[132:133]
	v_pk_add_f32 v[88:89], v[88:89], v[136:137]
	v_pk_add_f32 v[92:93], v[92:93], v[140:141]
	v_pk_add_f32 v[96:97], v[96:97], v[144:145]
	v_pk_add_f32 v[94:95], v[94:95], v[142:143]
	v_pk_add_f32 v[90:91], v[90:91], v[138:139]
	v_pk_add_f32 v[86:87], v[86:87], v[134:135]
	v_pk_add_f32 v[82:83], v[82:83], v[130:131]
	ds_read_b128 v[130:133], v166 offset:128
	ds_read_b128 v[134:137], v166 offset:144
	ds_read_b128 v[138:141], v166 offset:192
	ds_read_b128 v[142:145], v166 offset:208
	s_waitcnt lgkmcnt(0)
	v_pk_add_f32 v[100:101], v[100:101], v[132:133]
	v_pk_add_f32 v[104:105], v[104:105], v[136:137]
	v_pk_add_f32 v[108:109], v[108:109], v[140:141]
	v_pk_add_f32 v[112:113], v[112:113], v[144:145]
	v_pk_add_f32 v[110:111], v[110:111], v[142:143]
	v_pk_add_f32 v[106:107], v[106:107], v[138:139]
	v_pk_add_f32 v[102:103], v[102:103], v[134:135]
	v_pk_add_f32 v[98:99], v[98:99], v[130:131]
	s_branch .LBB0_291
.Lnear_u2o:
	v_add_u32_e32 v130, s20, v249
	v_add_u32_e32 v130, 0x6f, v130
	v_and_b32_e32 v130, 0x3ffffffc, v130
	v_lshl_add_u32 v162, v130, 2, v244
	ds_read_b128 v[130:133], v162
	ds_read_b128 v[134:137], v162 offset:16
	ds_read_b128 v[138:141], v162 offset:64
	ds_read_b128 v[142:145], v162 offset:80
	s_waitcnt lgkmcnt(0)
	v_pk_add_f32 v[84:85], v[84:85], v[132:133]
	v_pk_add_f32 v[86:87], v[86:87], v[134:135]
	v_pk_add_f32 v[90:91], v[90:91], v[138:139]
	v_pk_add_f32 v[94:95], v[94:95], v[142:143]
	v_pk_add_f32 v[96:97], v[96:97], v[144:145]
	v_pk_add_f32 v[92:93], v[92:93], v[140:141]
	v_pk_add_f32 v[88:89], v[88:89], v[136:137]
	v_pk_add_f32 v[82:83], v[82:83], v[130:131]
	ds_read_b128 v[130:133], v162 offset:128
	ds_read_b128 v[134:137], v162 offset:144
	ds_read_b128 v[138:141], v162 offset:192
	ds_read_b128 v[142:145], v162 offset:208
	s_waitcnt lgkmcnt(0)
	v_pk_add_f32 v[100:101], v[100:101], v[132:133]
	v_pk_add_f32 v[102:103], v[102:103], v[134:135]
	v_pk_add_f32 v[106:107], v[106:107], v[138:139]
	v_pk_add_f32 v[110:111], v[110:111], v[142:143]
	v_pk_add_f32 v[112:113], v[112:113], v[144:145]
	v_pk_add_f32 v[108:109], v[108:109], v[140:141]
	v_pk_add_f32 v[104:105], v[104:105], v[136:137]
	v_pk_add_f32 v[98:99], v[98:99], v[130:131]
	s_branch .LBB0_331
